# lru_fix: segment-carry loads issued together instead of one serialized round trip per segment
# speedup vs baseline: 1.0248x; 1.0011x over previous
; __device__ __forceinline__ int opaque_bid() { int t = blockIdx.x; asm volatile("" : "+s"(t)); return t; }
; __device__ __forceinline__ int opaque_gd() { int t = gridDim.x; asm volatile("" : "+s"(t)); return t; }
; __device__ __forceinline__ int opaque_tid() { int t = threadIdx.x; asm volatile("" : "+v"(t)); return t; }
; __device__ __forceinline__ Params fetchP(const LAS Params* lp0) { unsigned la = (unsigned)(unsigned long long)lp0; asm volatile("" : "+v"(la)); const LAS Params* lp = (const LAS Params*)la; Params q; PFIELDS(PFETCH) q.ph_lo = 0; q.ph_hi = 0; return q; }
; __device__ __forceinline__ void lru_fix_item(const Params& p, int l, int item) {
;     const int tid = opaque_tid(), wid = tid >> 6, lane = tid & 63;
;     const int b = item >> 6, h = (item >> 4) & 3, seg = item & 15;
;     const int t0 = seg * 128 + wid * 16; const size_t Tb = (size_t)b * SEQ;
;     const int ch = h * 64 + lane;
;     const float* sc = (const float*)p.hbuf + ((((size_t)b * 4 + h) * 16 + seg) * 8 + wid) * 2048 + lane * 16;
;     f32x4 hv[4], av[4]; unsigned gr[16];
; #pragma unroll
;     for (int q = 0; q < 4; ++q) { hv[q] = *(const f32x4*)(sc + q * 4); av[q] = *(const f32x4*)(sc + 1024 + q * 4); }
; #pragma unroll
;     for (int i = 0; i < 16; ++i) gr[i] = p.z[(Tb + t0 + i) * ZLD + 2560 + ch];
;     const float* car = p.lru_carry + (((size_t)b * 4 + h) * 16) * 128;
;     float Hin = 0.f;
; #pragma unroll 4
;     for (int s = 0; s < seg; ++s) { const float as = car[s * 128 + lane * 2], hs = car[s * 128 + lane * 2 + 1]; Hin = as * Hin + hs; }
; __device__ __forceinline__ void run_phase(const LAS Params* lp, int ph, LAS unsigned char* lds) {
;     ...
;     case 2: for (int it = opaque_bid(); it < 1280; it += opaque_gd()) { const Params p = fetchP(lp); const int jx = (it & ~255) + (it & 7) * 32 + ((it & 255) >> 3);
;             if (it < 256) hgrn_item(p, l, jx, 1, lds); else if (it < 768) gmlp_item(p, l, jx - 256, lds); else lru_fix_item(p, l, jx - 768); } break;
.LBB0_307:
	v_mov_b32_e32 v0, s84
	s_waitcnt vmcnt(0)
	ds_read2_b64 v[4:7], v0 offset0:8 offset1:9
	ds_read2_b64 v[8:11], v0 offset0:29 offset1:30
	s_lshl_b32 s7, s72, 5
	s_and_b32 s6, s72, 0xffffff00
	s_and_b32 s7, s7, 0xe0
	s_waitcnt lgkmcnt(0)
	v_readfirstlane_b32 s2, v4
	v_readfirstlane_b32 s20, v5
	v_readfirstlane_b32 s23, v6
	v_readfirstlane_b32 s36, v7
	ds_read2_b64 v[4:7], v0 offset0:11 offset1:31
	s_or_b32 s21, s7, s6
	v_readfirstlane_b32 s34, v8
	v_readfirstlane_b32 s35, v9
	v_readfirstlane_b32 s9, v10
	s_waitcnt lgkmcnt(0)
	v_readfirstlane_b32 s0, v4
	v_readfirstlane_b32 s14, v5
	v_readfirstlane_b32 s30, v6
	v_readfirstlane_b32 s31, v7
	ds_read2_b64 v[4:7], v0 offset0:33 offset1:37
	v_readfirstlane_b32 s33, v11
	s_mov_b64 s[6:7], -1
	s_cmpk_gt_i32 s72, 0xff
	s_waitcnt lgkmcnt(0)
	v_readfirstlane_b32 s4, v4
	v_readfirstlane_b32 s5, v5
	v_readfirstlane_b32 s18, v6
	v_readfirstlane_b32 s19, v7
	ds_read2_b64 v[4:7], v0 offset0:39 offset1:40
	ds_read_b64 v[0:1], v0 offset:328
	s_waitcnt lgkmcnt(1)
	v_readfirstlane_b32 s15, v4
	v_readfirstlane_b32 s17, v5
	v_readfirstlane_b32 s10, v6
	v_readfirstlane_b32 s11, v7
	s_waitcnt lgkmcnt(0)
	v_readfirstlane_b32 s12, v0
	v_readfirstlane_b32 s13, v1
	s_cbranch_scc0 .LBB0_326
	s_bfe_u32 s6, s72, 0x50003
	s_or_b32 s16, s21, s6
	s_cmpk_gt_u32 s72, 0x2ff
	s_mov_b64 s[6:7], -1
	s_cbranch_scc0 .LBB0_319
	s_add_i32 s6, s21, 0xfffffd00
	s_ashr_i32 s38, s6, 6
	s_bfe_u32 s37, s16, 0x20004
	s_ashr_i32 s39, s38, 31
	s_lshl_b64 s[6:7], s[38:39], 6
	s_lshl_b32 s8, s37, 4
	s_bfe_u32 s22, s72, 0x40003
	s_or_b32 s8, s6, s8
	s_or_b32 s6, s8, s22
	v_mov_b32_e32 v1, v202
	s_lshl_b64 s[40:41], s[6:7], 16
	s_add_u32 s40, s9, s40
	v_ashrrev_i32_e32 v0, 6, v1
	v_and_b32_e32 v36, 63, v1
	v_ashrrev_i32_e32 v1, 31, v0
	s_addc_u32 s41, s33, s41
	s_lshl_b32 s6, s22, 7
	v_lshlrev_b64 v[4:5], 13, v[0:1]
	v_lshl_add_u32 v0, v0, 4, s6
	s_lshl_b64 s[38:39], s[38:39], 11
	v_ashrrev_i32_e32 v1, 31, v0
	v_lshl_add_u64 v[4:5], s[40:41], 0, v[4:5]
	v_lshlrev_b32_e32 v6, 6, v36
	v_mov_b32_e32 v7, v2
	v_lshl_add_u64 v[38:39], s[38:39], 0, v[0:1]
	v_mov_b64_e32 v[0:1], s[34:35]
	s_movk_i32 s6, 0x1600
	v_lshl_add_u64 v[8:9], v[4:5], 0, v[6:7]
	s_mov_b64 s[40:41], 0x1000
	v_lshl_or_b32 v3, s37, 6, v36
	v_mad_u64_u32 v[40:41], s[38:39], v38, s6, v[0:1]
	v_lshl_add_u64 v[24:25], v[8:9], 0, s[40:41]
	global_load_dwordx4 v[4:7], v[8:9], off offset:48
	global_load_dwordx4 v[12:15], v[8:9], off offset:32
	global_load_dwordx4 v[20:23], v[8:9], off offset:16
	global_load_dwordx4 v[28:31], v[8:9], off
	v_add_co_u32_e32 v8, vcc, s80, v8
	v_mad_i32_i24 v41, v39, s6, v41
	v_lshlrev_b32_e32 v0, 1, v3
	v_mov_b32_e32 v1, v2
	v_addc_co_u32_e32 v9, vcc, 0, v9, vcc
	v_lshl_add_u64 v[40:41], v[40:41], 0, v[0:1]
	v_add_co_u32_e32 v42, vcc, s80, v40
	global_load_dwordx4 v[32:35], v[8:9], off
	s_nop 0
	global_load_dwordx4 v[8:11], v[24:25], off offset:48
	global_load_dwordx4 v[16:19], v[24:25], off offset:32
	s_nop 0
	global_load_dwordx4 v[24:27], v[24:25], off offset:16
	v_addc_co_u32_e32 v43, vcc, 0, v41, vcc
	global_load_ushort v1, v[42:43], off offset:1024
	v_add_co_u32_e32 v42, vcc, s81, v40
	s_movk_i32 s6, 0x4000
	s_nop 0
	v_addc_co_u32_e32 v43, vcc, 0, v41, vcc
	global_load_ushort v55, v[42:43], off offset:2560
	v_add_co_u32_e32 v42, vcc, s6, v40
	s_movk_i32 s6, 0x5000
	s_nop 0
	v_addc_co_u32_e32 v43, vcc, 0, v41, vcc
	global_load_ushort v54, v[42:43], off
	v_add_co_u32_e32 v42, vcc, s6, v40
	s_movk_i32 s6, 0x6000
	s_nop 0
	v_addc_co_u32_e32 v43, vcc, 0, v41, vcc
	global_load_ushort v53, v[42:43], off offset:1536
	v_add_co_u32_e32 v42, vcc, s6, v40
	s_mov_b32 s6, 0x8000
	s_nop 0
	v_addc_co_u32_e32 v43, vcc, 0, v41, vcc
	global_load_ushort v52, v[42:43], off offset:3072
	v_add_co_u32_e32 v42, vcc, s6, v40
	s_mov_b32 s6, 0x9000
	s_nop 0
	v_addc_co_u32_e32 v43, vcc, 0, v41, vcc
	global_load_ushort v51, v[42:43], off offset:512
	v_add_co_u32_e32 v42, vcc, s6, v40
	s_mov_b32 s6, 0xa000
	s_nop 0
	v_addc_co_u32_e32 v43, vcc, 0, v41, vcc
	global_load_ushort v50, v[42:43], off offset:2048
	v_add_co_u32_e32 v42, vcc, s6, v40
	s_mov_b32 s6, 0xc000
	s_nop 0
	v_addc_co_u32_e32 v43, vcc, 0, v41, vcc
	global_load_ushort v49, v[42:43], off offset:3584
	v_add_co_u32_e32 v42, vcc, s6, v40
	s_mov_b32 s6, 0xd000
	s_nop 0
	v_addc_co_u32_e32 v43, vcc, 0, v41, vcc
	global_load_ushort v48, v[42:43], off offset:1024
	v_add_co_u32_e32 v42, vcc, s6, v40
	s_mov_b32 s6, 0xf000
	s_nop 0
	v_addc_co_u32_e32 v43, vcc, 0, v41, vcc
	global_load_ushort v47, v[42:43], off offset:2560
	v_add_co_u32_e32 v42, vcc, s6, v40
	s_mov_b32 s6, 0x10000
	s_nop 0
	v_addc_co_u32_e32 v43, vcc, 0, v41, vcc
	global_load_ushort v46, v[42:43], off
	v_add_co_u32_e32 v42, vcc, s6, v40
	s_cmp_eq_u32 s22, 0
	s_nop 0
	v_addc_co_u32_e32 v43, vcc, 0, v41, vcc
	global_load_ushort v45, v[42:43], off offset:1536
	v_add_co_u32_e32 v42, vcc, 0x11000, v40
	s_nop 1
	v_addc_co_u32_e32 v43, vcc, 0, v41, vcc
	global_load_ushort v44, v[42:43], off offset:3072
	v_add_co_u32_e32 v42, vcc, 0x13000, v40
	s_nop 1
	v_addc_co_u32_e32 v43, vcc, 0, v41, vcc
	v_add_co_u32_e32 v56, vcc, 0x14000, v40
	global_load_ushort v43, v[42:43], off offset:512
	s_nop 0
	v_addc_co_u32_e32 v57, vcc, 0, v41, vcc
	v_add_co_u32_e32 v40, vcc, 0x15000, v40
	global_load_ushort v42, v[56:57], off offset:2048
	s_nop 0
	v_addc_co_u32_e32 v41, vcc, 0, v41, vcc
	global_load_ushort v3, v[40:41], off offset:3584
	s_cbranch_scc1 .LBB0_314
	s_mov_b32 s9, s7
	s_lshl_b64 s[6:7], s[8:9], 9
	s_add_u32 s6, s15, s6
	s_addc_u32 s7, s17, s7
	v_lshlrev_b32_e32 v56, 3, v36
	s_mov_b32 s38, 0x16000
	s_add_u32 s8, s6, 0x1000
	s_addc_u32 s9, s7, 0
	s_cmp_le_u32 s22, 0
	s_cbranch_scc1 .Llrufix_issued
; __device__ __forceinline__ bf16_t f2bf(float f) { return (bf16_t)(pk2(f, 0.f) & 0xffffu); }
; __device__ __forceinline__ float bf2f(unsigned b) { return __uint_as_float(b << 16); }
; __device__ __forceinline__ float gelu_t(float x) { return x * sigm(1.5957691216057308f * (x + 0.044715f * x * x * x)); }
; __device__ __forceinline__ void lru_fix_item(const Params& p, int l, int item) {
;     ...
;     const float* car = p.lru_carry + (((size_t)b * 4 + h) * 16) * 128;
;     float Hin = 0.f;
; #pragma unroll 4
;     for (int s = 0; s < seg; ++s) { const float as = car[s * 128 + lane * 2], hs = car[s * 128 + lane * 2 + 1]; Hin = as * Hin + hs; }
; #pragma unroll
;     for (int i = 0; i < 16; ++i) { const float hvv = hv[i >> 2][i & 3] + av[i >> 2][i & 3] * Hin; const size_t T = Tb + t0 + i;
;         p.outs[((size_t)3 * M + T) * 256 + ch] = f2bf(hvv * gelu_t(bf2f(gr[i]))); }
	global_load_dwordx2 v[62:63], v56, s[6:7] offset:0
	s_cmp_le_u32 s22, 1
	s_cbranch_scc1 .Llrufix_issued
	global_load_dwordx2 v[64:65], v56, s[6:7] offset:512
	s_cmp_le_u32 s22, 2
	s_cbranch_scc1 .Llrufix_issued
	global_load_dwordx2 v[66:67], v56, s[6:7] offset:1024
	s_cmp_le_u32 s22, 3
	s_cbranch_scc1 .Llrufix_issued
	global_load_dwordx2 v[68:69], v56, s[6:7] offset:1536
	s_cmp_le_u32 s22, 4
	s_cbranch_scc1 .Llrufix_issued
	global_load_dwordx2 v[70:71], v56, s[6:7] offset:2048
	s_cmp_le_u32 s22, 5
	s_cbranch_scc1 .Llrufix_issued
	global_load_dwordx2 v[72:73], v56, s[6:7] offset:2560
	s_cmp_le_u32 s22, 6
	s_cbranch_scc1 .Llrufix_issued
	global_load_dwordx2 v[74:75], v56, s[6:7] offset:3072
	s_cmp_le_u32 s22, 7
	s_cbranch_scc1 .Llrufix_issued
	global_load_dwordx2 v[76:77], v56, s[6:7] offset:3584
	s_cmp_le_u32 s22, 8
	s_cbranch_scc1 .Llrufix_issued
	global_load_dwordx2 v[78:79], v56, s[8:9] offset:0
	s_cmp_le_u32 s22, 9
	s_cbranch_scc1 .Llrufix_issued
	global_load_dwordx2 v[80:81], v56, s[8:9] offset:512
	s_cmp_le_u32 s22, 10
	s_cbranch_scc1 .Llrufix_issued
	global_load_dwordx2 v[82:83], v56, s[8:9] offset:1024
	s_cmp_le_u32 s22, 11
	s_cbranch_scc1 .Llrufix_issued
	global_load_dwordx2 v[84:85], v56, s[8:9] offset:1536
	s_cmp_le_u32 s22, 12
	s_cbranch_scc1 .Llrufix_issued
	global_load_dwordx2 v[86:87], v56, s[8:9] offset:2048
	s_cmp_le_u32 s22, 13
	s_cbranch_scc1 .Llrufix_issued
	global_load_dwordx2 v[88:89], v56, s[8:9] offset:2560
	s_cmp_le_u32 s22, 14
	s_cbranch_scc1 .Llrufix_issued
	global_load_dwordx2 v[90:91], v56, s[8:9] offset:3072
.Llrufix_issued:
	v_mov_b32_e32 v37, 0
	s_waitcnt vmcnt(0)
	s_cmp_le_u32 s22, 0
	s_cbranch_scc1 .LBB0_318
	v_fma_f32 v37, v37, v62, v63
	s_cmp_le_u32 s22, 1
	s_cbranch_scc1 .LBB0_318
	v_fma_f32 v37, v37, v64, v65
	s_cmp_le_u32 s22, 2
	s_cbranch_scc1 .LBB0_318
	v_fma_f32 v37, v37, v66, v67
	s_cmp_le_u32 s22, 3
	s_cbranch_scc1 .LBB0_318
	v_fma_f32 v37, v37, v68, v69
	s_cmp_le_u32 s22, 4
	s_cbranch_scc1 .LBB0_318
	v_fma_f32 v37, v37, v70, v71
	s_cmp_le_u32 s22, 5
	s_cbranch_scc1 .LBB0_318
	v_fma_f32 v37, v37, v72, v73
	s_cmp_le_u32 s22, 6
	s_cbranch_scc1 .LBB0_318
	v_fma_f32 v37, v37, v74, v75
	s_cmp_le_u32 s22, 7
	s_cbranch_scc1 .LBB0_318
	v_fma_f32 v37, v37, v76, v77
	s_cmp_le_u32 s22, 8
	s_cbranch_scc1 .LBB0_318
	v_fma_f32 v37, v37, v78, v79
	s_cmp_le_u32 s22, 9
	s_cbranch_scc1 .LBB0_318
	v_fma_f32 v37, v37, v80, v81
	s_cmp_le_u32 s22, 10
	s_cbranch_scc1 .LBB0_318
	v_fma_f32 v37, v37, v82, v83
	s_cmp_le_u32 s22, 11
	s_cbranch_scc1 .LBB0_318
	v_fma_f32 v37, v37, v84, v85
	s_cmp_le_u32 s22, 12
	s_cbranch_scc1 .LBB0_318
	v_fma_f32 v37, v37, v86, v87
	s_cmp_le_u32 s22, 13
	s_cbranch_scc1 .LBB0_318
	v_fma_f32 v37, v37, v88, v89
	s_cmp_le_u32 s22, 14
	s_cbranch_scc1 .LBB0_318
	v_fma_f32 v37, v37, v90, v91
	s_branch .LBB0_318
.LBB0_314:
	v_mov_b32_e32 v37, 0
	s_mov_b32 s38, 0x16000
.LBB0_318:
	s_waitcnt vmcnt(15)
	v_lshlrev_b32_e32 v1, 16, v1
	v_fma_f32 v28, v32, v37, v28
	v_mul_f32_e32 v32, 0x3d372713, v1
	v_mul_f32_e32 v32, v32, v1
	v_fma_f32 v32, v32, v1, v1
	v_mul_f32_e32 v32, 0x3fcc422a, v32
	v_mul_f32_e32 v32, 0xbfb8aa3b, v32
	v_exp_f32_e32 v32, v32
	v_lshlrev_b64 v[38:39], 9, v[38:39]
	v_lshl_add_u64 v[40:41], s[30:31], 0, v[38:39]
	s_mov_b32 s6, 0x1800000
	v_add_f32_e32 v32, 1.0, v32
	v_rcp_f32_e32 v32, v32
	v_fmac_f32_e32 v31, v35, v37
	v_fma_f32 v20, v24, v37, v20
	s_waitcnt vmcnt(11)
	v_lshlrev_b32_e32 v24, 16, v52
	v_mul_f32_e32 v1, v32, v1
	v_mul_f32_e32 v1, v1, v28
	v_cvt_pk_bf16_f32 v28, v1, v2
	v_mov_b32_e32 v1, v2
	v_lshl_add_u64 v[40:41], v[40:41], 0, v[0:1]
	v_add_co_u32_e32 v40, vcc, s6, v40
	v_fmac_f32_e32 v23, v27, v37
	s_nop 0
	v_addc_co_u32_e32 v41, vcc, 0, v41, vcc
	global_store_short v[40:41], v28, off
	v_fma_f32 v28, v33, v37, v29
	v_lshlrev_b32_e32 v29, 16, v55
	v_mul_f32_e32 v32, 0x3d372713, v29
	v_mul_f32_e32 v32, v32, v29
	v_fma_f32 v32, v32, v29, v29
	v_mul_f32_e32 v32, 0x3fcc422a, v32
	v_mul_f32_e32 v32, 0xbfb8aa3b, v32
	v_exp_f32_e32 v32, v32
	v_fma_f32 v12, v16, v37, v12
	s_waitcnt vmcnt(8)
	v_lshlrev_b32_e32 v16, 16, v48
	v_fmac_f32_e32 v15, v19, v37
	v_add_f32_e32 v32, 1.0, v32
	v_rcp_f32_e32 v32, v32
	v_fma_f32 v4, v8, v37, v4
	s_waitcnt vmcnt(4)
	v_lshlrev_b32_e32 v8, 16, v44
	s_waitcnt vmcnt(1)
; __device__ __forceinline__ bf16_t f2bf(float f) { return (bf16_t)(pk2(f, 0.f) & 0xffffu); }
; __device__ __forceinline__ float bf2f(unsigned b) { return __uint_as_float(b << 16); }
; __device__ __forceinline__ float fexp(float x) { return __builtin_amdgcn_exp2f(x * LOG2E); }
; __device__ __forceinline__ float frcp(float x) { return __builtin_amdgcn_rcpf(x); }
; __device__ __forceinline__ float sigm(float x) { return frcp(1.f + fexp(-x)); }
; __device__ __forceinline__ float silu(float x) { return x * sigm(x); }
; __device__ __forceinline__ float gelu_t(float x) { return x * sigm(1.5957691216057308f * (x + 0.044715f * x * x * x)); }
; __device__ __forceinline__ void lru_fix_item(const Params& p, int l, int item) {
;     ...
;     for (int i = 0; i < 16; ++i) { const float hvv = hv[i >> 2][i & 3] + av[i >> 2][i & 3] * Hin; const size_t T = Tb + t0 + i;
;         p.outs[((size_t)3 * M + T) * 256 + ch] = f2bf(hvv * gelu_t(bf2f(gr[i]))); }
	v_lshlrev_b32_e32 v3, 16, v3
	v_mul_f32_e32 v29, v32, v29
	v_mul_f32_e32 v28, v29, v28
	v_cvt_pk_bf16_f32 v32, v28, v2
	v_or_b32_e32 v28, 0x200, v38
	v_mov_b32_e32 v29, v39
	v_lshl_add_u64 v[28:29], s[30:31], 0, v[28:29]
	v_lshl_add_u64 v[28:29], v[28:29], 0, v[0:1]
	v_add_co_u32_e32 v28, vcc, s6, v28
	v_fmac_f32_e32 v7, v11, v37
	s_nop 0
	v_addc_co_u32_e32 v29, vcc, 0, v29, vcc
	global_store_short v[28:29], v32, off
	v_lshlrev_b32_e32 v29, 16, v54
	v_fma_f32 v28, v34, v37, v30
	v_mul_f32_e32 v30, 0x3d372713, v29
	v_mul_f32_e32 v30, v30, v29
	v_fma_f32 v30, v30, v29, v29
	v_mul_f32_e32 v30, 0x3fcc422a, v30
	v_mul_f32_e32 v30, 0xbfb8aa3b, v30
	v_exp_f32_e32 v30, v30
	s_nop 0
	v_add_f32_e32 v30, 1.0, v30
	v_rcp_f32_e32 v30, v30
	s_nop 0
	v_mul_f32_e32 v29, v30, v29
	v_mul_f32_e32 v28, v29, v28
	v_cvt_pk_bf16_f32 v30, v28, v2
	v_or_b32_e32 v28, 0x400, v38
	v_mov_b32_e32 v29, v39
	v_lshl_add_u64 v[28:29], s[30:31], 0, v[28:29]
	v_lshl_add_u64 v[28:29], v[28:29], 0, v[0:1]
	v_add_co_u32_e32 v28, vcc, s6, v28
	s_nop 1
	v_addc_co_u32_e32 v29, vcc, 0, v29, vcc
	global_store_short v[28:29], v30, off
	v_lshlrev_b32_e32 v28, 16, v53
	v_mul_f32_e32 v29, 0x3d372713, v28
	v_mul_f32_e32 v29, v29, v28
	v_fma_f32 v29, v29, v28, v28
	v_mul_f32_e32 v29, 0x3fcc422a, v29
	v_mul_f32_e32 v29, 0xbfb8aa3b, v29
	v_exp_f32_e32 v29, v29
	s_nop 0
	v_add_f32_e32 v29, 1.0, v29
	v_rcp_f32_e32 v29, v29
	s_nop 0
	v_mul_f32_e32 v28, v29, v28
	v_mul_f32_e32 v28, v28, v31
	v_cvt_pk_bf16_f32 v30, v28, v2
	v_or_b32_e32 v28, 0x600, v38
	v_mov_b32_e32 v29, v39
	v_lshl_add_u64 v[28:29], s[30:31], 0, v[28:29]
	v_lshl_add_u64 v[28:29], v[28:29], 0, v[0:1]
	v_add_co_u32_e32 v28, vcc, s6, v28
	s_nop 1
	v_addc_co_u32_e32 v29, vcc, 0, v29, vcc
	global_store_short v[28:29], v30, off
	v_mul_f32_e32 v28, 0x3d372713, v24
	v_mul_f32_e32 v28, v28, v24
	v_fma_f32 v28, v28, v24, v24
	v_mul_f32_e32 v28, 0x3fcc422a, v28
	v_mul_f32_e32 v28, 0xbfb8aa3b, v28
	v_exp_f32_e32 v28, v28
	v_mov_b32_e32 v29, v39
	v_add_f32_e32 v28, 1.0, v28
	v_rcp_f32_e32 v28, v28
	s_nop 0
	v_mul_f32_e32 v24, v28, v24
	v_or_b32_e32 v28, 0x800, v38
	v_lshl_add_u64 v[28:29], s[30:31], 0, v[28:29]
	v_lshl_add_u64 v[28:29], v[28:29], 0, v[0:1]
	v_mul_f32_e32 v20, v24, v20
	v_add_co_u32_e32 v28, vcc, s6, v28
	v_cvt_pk_bf16_f32 v20, v20, v2
	s_nop 1
	v_addc_co_u32_e32 v29, vcc, 0, v29, vcc
	global_store_short v[28:29], v20, off
	v_fma_f32 v20, v25, v37, v21
	v_lshlrev_b32_e32 v21, 16, v51
	v_mul_f32_e32 v24, 0x3d372713, v21
	v_mul_f32_e32 v24, v24, v21
	v_fma_f32 v24, v24, v21, v21
	v_mul_f32_e32 v24, 0x3fcc422a, v24
	v_mul_f32_e32 v24, 0xbfb8aa3b, v24
	v_exp_f32_e32 v24, v24
	s_nop 0
	v_add_f32_e32 v24, 1.0, v24
	v_rcp_f32_e32 v24, v24
	s_nop 0
	v_mul_f32_e32 v21, v24, v21
	v_mul_f32_e32 v20, v21, v20
	v_cvt_pk_bf16_f32 v24, v20, v2
	v_or_b32_e32 v20, 0xa00, v38
	v_mov_b32_e32 v21, v39
	v_lshl_add_u64 v[20:21], s[30:31], 0, v[20:21]
	v_lshl_add_u64 v[20:21], v[20:21], 0, v[0:1]
	v_add_co_u32_e32 v20, vcc, s6, v20
	s_nop 1
	v_addc_co_u32_e32 v21, vcc, 0, v21, vcc
	global_store_short v[20:21], v24, off
	v_lshlrev_b32_e32 v21, 16, v50
	v_fma_f32 v20, v26, v37, v22
	v_mul_f32_e32 v22, 0x3d372713, v21
	v_mul_f32_e32 v22, v22, v21
	v_fma_f32 v22, v22, v21, v21
	v_mul_f32_e32 v22, 0x3fcc422a, v22
	v_mul_f32_e32 v22, 0xbfb8aa3b, v22
	v_exp_f32_e32 v22, v22
	s_nop 0
	v_add_f32_e32 v22, 1.0, v22
	v_rcp_f32_e32 v22, v22
	s_nop 0
	v_mul_f32_e32 v21, v22, v21
	v_mul_f32_e32 v20, v21, v20
	v_cvt_pk_bf16_f32 v22, v20, v2
	v_or_b32_e32 v20, 0xc00, v38
	v_mov_b32_e32 v21, v39
	v_lshl_add_u64 v[20:21], s[30:31], 0, v[20:21]
	v_lshl_add_u64 v[20:21], v[20:21], 0, v[0:1]
	v_add_co_u32_e32 v20, vcc, s6, v20
	s_nop 1
	v_addc_co_u32_e32 v21, vcc, 0, v21, vcc
	global_store_short v[20:21], v22, off
	v_lshlrev_b32_e32 v20, 16, v49
	v_mul_f32_e32 v21, 0x3d372713, v20
	v_mul_f32_e32 v21, v21, v20
	v_fma_f32 v21, v21, v20, v20
	v_mul_f32_e32 v21, 0x3fcc422a, v21
	v_mul_f32_e32 v21, 0xbfb8aa3b, v21
	v_exp_f32_e32 v21, v21
	s_nop 0
	v_add_f32_e32 v21, 1.0, v21
	v_rcp_f32_e32 v21, v21
	s_nop 0
	v_mul_f32_e32 v20, v21, v20
	v_mul_f32_e32 v20, v20, v23
	v_cvt_pk_bf16_f32 v22, v20, v2
	v_or_b32_e32 v20, 0xe00, v38
	v_mov_b32_e32 v21, v39
	v_lshl_add_u64 v[20:21], s[30:31], 0, v[20:21]
	v_lshl_add_u64 v[20:21], v[20:21], 0, v[0:1]
	v_add_co_u32_e32 v20, vcc, s6, v20
	s_nop 1
	v_addc_co_u32_e32 v21, vcc, 0, v21, vcc
	global_store_short v[20:21], v22, off
	v_mul_f32_e32 v20, 0x3d372713, v16
	v_mul_f32_e32 v20, v20, v16
	v_fma_f32 v20, v20, v16, v16
	v_mul_f32_e32 v20, 0x3fcc422a, v20
	v_mul_f32_e32 v20, 0xbfb8aa3b, v20
	v_exp_f32_e32 v20, v20
	v_mov_b32_e32 v21, v39
	v_add_f32_e32 v20, 1.0, v20
	v_rcp_f32_e32 v20, v20
	s_nop 0
	v_mul_f32_e32 v16, v20, v16
	v_or_b32_e32 v20, 0x1000, v38
; __device__ __forceinline__ bf16_t f2bf(float f) { return (bf16_t)(pk2(f, 0.f) & 0xffffu); }
; __device__ __forceinline__ float bf2f(unsigned b) { return __uint_as_float(b << 16); }
; __device__ __forceinline__ float fexp(float x) { return __builtin_amdgcn_exp2f(x * LOG2E); }
; __device__ __forceinline__ float frcp(float x) { return __builtin_amdgcn_rcpf(x); }
; __device__ __forceinline__ float sigm(float x) { return frcp(1.f + fexp(-x)); }
; __device__ __forceinline__ float silu(float x) { return x * sigm(x); }
; __device__ __forceinline__ float gelu_t(float x) { return x * sigm(1.5957691216057308f * (x + 0.044715f * x * x * x)); }
; __device__ __forceinline__ void lru_fix_item(const Params& p, int l, int item) {
;     ...
;     for (int i = 0; i < 16; ++i) { const float hvv = hv[i >> 2][i & 3] + av[i >> 2][i & 3] * Hin; const size_t T = Tb + t0 + i;
;         p.outs[((size_t)3 * M + T) * 256 + ch] = f2bf(hvv * gelu_t(bf2f(gr[i]))); }
	v_lshl_add_u64 v[20:21], s[30:31], 0, v[20:21]
	v_lshl_add_u64 v[20:21], v[20:21], 0, v[0:1]
	v_mul_f32_e32 v12, v16, v12
	v_add_co_u32_e32 v20, vcc, s6, v20
	v_cvt_pk_bf16_f32 v12, v12, v2
	s_nop 1
	v_addc_co_u32_e32 v21, vcc, 0, v21, vcc
	global_store_short v[20:21], v12, off
	v_fma_f32 v12, v17, v37, v13
	v_lshlrev_b32_e32 v13, 16, v47
	v_mul_f32_e32 v16, 0x3d372713, v13
	v_mul_f32_e32 v16, v16, v13
	v_fma_f32 v16, v16, v13, v13
	v_mul_f32_e32 v16, 0x3fcc422a, v16
	v_mul_f32_e32 v16, 0xbfb8aa3b, v16
	v_exp_f32_e32 v16, v16
	s_nop 0
	v_add_f32_e32 v16, 1.0, v16
	v_rcp_f32_e32 v16, v16
	s_nop 0
	v_mul_f32_e32 v13, v16, v13
	v_mul_f32_e32 v12, v13, v12
	v_cvt_pk_bf16_f32 v16, v12, v2
	v_or_b32_e32 v12, 0x1200, v38
	v_mov_b32_e32 v13, v39
	v_lshl_add_u64 v[12:13], s[30:31], 0, v[12:13]
	v_lshl_add_u64 v[12:13], v[12:13], 0, v[0:1]
	v_add_co_u32_e32 v12, vcc, s6, v12
	s_nop 1
	v_addc_co_u32_e32 v13, vcc, 0, v13, vcc
	global_store_short v[12:13], v16, off
	v_lshlrev_b32_e32 v13, 16, v46
	v_fma_f32 v12, v18, v37, v14
	v_mul_f32_e32 v14, 0x3d372713, v13
	v_mul_f32_e32 v14, v14, v13
	v_fma_f32 v14, v14, v13, v13
	v_mul_f32_e32 v14, 0x3fcc422a, v14
	v_mul_f32_e32 v14, 0xbfb8aa3b, v14
	v_exp_f32_e32 v14, v14
	s_nop 0
	v_add_f32_e32 v14, 1.0, v14
	v_rcp_f32_e32 v14, v14
	s_nop 0
	v_mul_f32_e32 v13, v14, v13
	v_mul_f32_e32 v12, v13, v12
	v_cvt_pk_bf16_f32 v14, v12, v2
	v_or_b32_e32 v12, 0x1400, v38
	v_mov_b32_e32 v13, v39
	v_lshl_add_u64 v[12:13], s[30:31], 0, v[12:13]
	v_lshl_add_u64 v[12:13], v[12:13], 0, v[0:1]
	v_add_co_u32_e32 v12, vcc, s6, v12
	s_nop 1
	v_addc_co_u32_e32 v13, vcc, 0, v13, vcc
	global_store_short v[12:13], v14, off
	v_lshlrev_b32_e32 v12, 16, v45
	v_mul_f32_e32 v13, 0x3d372713, v12
	v_mul_f32_e32 v13, v13, v12
	v_fma_f32 v13, v13, v12, v12
	v_mul_f32_e32 v13, 0x3fcc422a, v13
	v_mul_f32_e32 v13, 0xbfb8aa3b, v13
	v_exp_f32_e32 v13, v13
	s_nop 0
	v_add_f32_e32 v13, 1.0, v13
	v_rcp_f32_e32 v13, v13
	s_nop 0
	v_mul_f32_e32 v12, v13, v12
	v_mul_f32_e32 v12, v12, v15
	v_cvt_pk_bf16_f32 v14, v12, v2
	v_or_b32_e32 v12, 0x1600, v38
	v_mov_b32_e32 v13, v39
	v_lshl_add_u64 v[12:13], s[30:31], 0, v[12:13]
	v_lshl_add_u64 v[12:13], v[12:13], 0, v[0:1]
	v_add_co_u32_e32 v12, vcc, s6, v12
	s_nop 1
	v_addc_co_u32_e32 v13, vcc, 0, v13, vcc
	global_store_short v[12:13], v14, off
	v_mul_f32_e32 v12, 0x3d372713, v8
	v_mul_f32_e32 v12, v12, v8
	v_fma_f32 v12, v12, v8, v8
	v_mul_f32_e32 v12, 0x3fcc422a, v12
	v_mul_f32_e32 v12, 0xbfb8aa3b, v12
	v_exp_f32_e32 v12, v12
	v_mov_b32_e32 v13, v39
	v_add_f32_e32 v12, 1.0, v12
	v_rcp_f32_e32 v12, v12
	s_nop 0
	v_mul_f32_e32 v8, v12, v8
	v_or_b32_e32 v12, 0x1800, v38
	v_lshl_add_u64 v[12:13], s[30:31], 0, v[12:13]
	v_lshl_add_u64 v[12:13], v[12:13], 0, v[0:1]
	v_mul_f32_e32 v4, v8, v4
	v_add_co_u32_e32 v12, vcc, s6, v12
	v_cvt_pk_bf16_f32 v4, v4, v2
	s_nop 1
	v_addc_co_u32_e32 v13, vcc, 0, v13, vcc
	global_store_short v[12:13], v4, off
	v_fma_f32 v4, v9, v37, v5
	v_lshlrev_b32_e32 v5, 16, v43
	v_mul_f32_e32 v8, 0x3d372713, v5
	v_mul_f32_e32 v8, v8, v5
	v_fma_f32 v8, v8, v5, v5
	v_mul_f32_e32 v8, 0x3fcc422a, v8
	v_mul_f32_e32 v8, 0xbfb8aa3b, v8
	v_exp_f32_e32 v8, v8
	s_nop 0
	v_add_f32_e32 v8, 1.0, v8
	v_rcp_f32_e32 v8, v8
	s_nop 0
	v_mul_f32_e32 v5, v8, v5
	v_mul_f32_e32 v4, v5, v4
	v_cvt_pk_bf16_f32 v8, v4, v2
	v_or_b32_e32 v4, 0x1a00, v38
	v_mov_b32_e32 v5, v39
	v_lshl_add_u64 v[4:5], s[30:31], 0, v[4:5]
	v_lshl_add_u64 v[4:5], v[4:5], 0, v[0:1]
	v_add_co_u32_e32 v4, vcc, s6, v4
	s_nop 1
	v_addc_co_u32_e32 v5, vcc, 0, v5, vcc
	global_store_short v[4:5], v8, off
	v_lshlrev_b32_e32 v5, 16, v42
	v_fma_f32 v4, v10, v37, v6
	v_mul_f32_e32 v6, 0x3d372713, v5
	v_mul_f32_e32 v6, v6, v5
	v_fma_f32 v6, v6, v5, v5
	v_mul_f32_e32 v6, 0x3fcc422a, v6
	v_mul_f32_e32 v6, 0xbfb8aa3b, v6
	v_exp_f32_e32 v6, v6
	s_nop 0
	v_add_f32_e32 v6, 1.0, v6
	v_rcp_f32_e32 v6, v6
	s_nop 0
	v_mul_f32_e32 v5, v6, v5
	v_mul_f32_e32 v4, v5, v4
	v_cvt_pk_bf16_f32 v6, v4, v2
	v_or_b32_e32 v4, 0x1c00, v38
	v_mov_b32_e32 v5, v39
	v_lshl_add_u64 v[4:5], s[30:31], 0, v[4:5]
	v_lshl_add_u64 v[4:5], v[4:5], 0, v[0:1]
	v_add_co_u32_e32 v4, vcc, s6, v4
	v_or_b32_e32 v38, 0x1e00, v38
	s_nop 0
	v_addc_co_u32_e32 v5, vcc, 0, v5, vcc
	global_store_short v[4:5], v6, off
	v_mul_f32_e32 v4, 0x3d372713, v3
	v_mul_f32_e32 v4, v4, v3
	v_fma_f32 v4, v4, v3, v3
	v_mul_f32_e32 v4, 0x3fcc422a, v4
	v_mul_f32_e32 v4, 0xbfb8aa3b, v4
	v_exp_f32_e32 v4, v4
	s_mov_b64 s[6:7], 0
	v_add_f32_e32 v4, 1.0, v4
	v_rcp_f32_e32 v4, v4
	s_nop 0
	v_mul_f32_e32 v3, v4, v3
	v_lshl_add_u64 v[4:5], s[30:31], 0, v[38:39]
	v_lshl_add_u64 v[0:1], v[4:5], 0, v[0:1]
	v_add_co_u32_e32 v0, vcc, 0x1800000, v0
	v_mul_f32_e32 v3, v3, v7
	s_nop 0
	v_addc_co_u32_e32 v1, vcc, 0, v1, vcc
	v_cvt_pk_bf16_f32 v3, v3, v2
	global_store_short v[0:1], v3, off
